# attention loops: QK^T and PV fragment reads issued ahead with counted LDS waits (B, C, A); dead SGPR reloads dropped
# speedup vs baseline: 1.0210x; 1.0210x over previous
; __device__ __forceinline__ f32x4 mfma16(bf16x8 a, bf16x8 b, f32x4 c) { return __builtin_amdgcn_mfma_f32_16x16x32_bf16(a, b, c, 0, 0, 0); }
; template <int DQK, int DV, int MODE> ...
;     ...
; #pragma unroll
;         for (int t = 0; t < 4; ++t) {
;           {
;             const bf16x8 kf = *(const bf16x8*)(Ks + (t * 16 + fr) * KST + fq * 8);
; #pragma unroll
;             for (int qq = 0; qq < QG; ++qq) S[qq][t] = __builtin_amdgcn_mfma_f32_16x16x32_bf16(kf, *(const bf16x8*)(Qs2 + ((q0 + qq) * NKS) * 512), (f32x4){0.f, 0.f, 0.f, 0.f}, 0, 0, 0);
;           }
; #pragma unroll
;           for (int ks = 1; ks < NKS; ++ks) {
;             const bf16x8 kf = *(const bf16x8*)(Ks + (t * 16 + fr) * KST + ks * 32 + fq * 8);
; #pragma unroll
;             for (int qq = 0; qq < QG; ++qq) S[qq][t] = mfma16(kf, *(const bf16x8*)(Qs2 + ((q0 + qq) * NKS + ks) * 512), S[qq][t]);
;           }
;         }
.LBB0_538:
	s_or_b64 exec, exec, s[4:5]
	ds_read_b128 v[166:169], v124
	ds_read_b128 v[174:177], v124 offset:2048
	ds_read_b128 v[110:113], v207
	ds_read_b128 v[170:173], v124 offset:1024
	ds_read_b128 v[178:181], v124 offset:3072
	ds_read_b128 v[182:185], v207 offset:64
	ds_read_b128 v[106:109], v207 offset:2560
	ds_read_b128 v[186:189], v207 offset:2624
	ds_read_b128 v[102:105], v207 offset:5120
	ds_read_b128 v[94:97], v207 offset:7680
	s_xor_b64 s[4:5], s[12:13], -1
	v_cmp_gt_i32_e32 vcc, s26, v226
	s_waitcnt lgkmcnt(7)
	v_mfma_f32_16x16x32_bf16 v[98:101], v[110:113], v[166:169], 0
	v_mfma_f32_16x16x32_bf16 v[110:113], v[110:113], v[174:177], 0
	s_waitcnt lgkmcnt(4)
	v_mfma_f32_16x16x32_bf16 v[98:101], v[182:185], v[170:173], v[98:101]
	v_mfma_f32_16x16x32_bf16 v[110:113], v[182:185], v[178:181], v[110:113]
	ds_read_b128 v[182:185], v207 offset:5184
	s_waitcnt lgkmcnt(4)
	v_mfma_f32_16x16x32_bf16 v[118:121], v[106:109], v[166:169], 0
	v_mfma_f32_16x16x32_bf16 v[106:109], v[106:109], v[174:177], 0
	s_waitcnt lgkmcnt(3)
	v_mfma_f32_16x16x32_bf16 v[118:121], v[186:189], v[170:173], v[118:121]
	v_mfma_f32_16x16x32_bf16 v[106:109], v[186:189], v[178:181], v[106:109]
	ds_read_b128 v[186:189], v207 offset:7744
	s_waitcnt lgkmcnt(3)
	v_mfma_f32_16x16x32_bf16 v[90:93], v[102:105], v[166:169], 0
	v_mfma_f32_16x16x32_bf16 v[102:105], v[102:105], v[174:177], 0
	s_waitcnt lgkmcnt(1)
	v_mfma_f32_16x16x32_bf16 v[90:93], v[182:185], v[170:173], v[90:93]
	v_mfma_f32_16x16x32_bf16 v[102:105], v[182:185], v[178:181], v[102:105]
	v_mfma_f32_16x16x32_bf16 v[114:117], v[94:97], v[166:169], 0
	v_mfma_f32_16x16x32_bf16 v[94:97], v[94:97], v[174:177], 0
	s_waitcnt lgkmcnt(0)
	v_mfma_f32_16x16x32_bf16 v[114:117], v[186:189], v[170:173], v[114:117]
	v_mfma_f32_16x16x32_bf16 v[94:97], v[186:189], v[178:181], v[94:97]
	v_add_u32_e32 v246, v222, v232
	s_and_saveexec_b64 s[12:13], s[4:5]
	s_xor_b64 s[20:21], exec, s[12:13]
	s_cbranch_execz .LBB0_540
	s_cbranch_vccz .Lb1a_q1
; __device__ __forceinline__ float fmax3(float a, float b, float c) { float r; asm("v_max3_f32 %0, %1, %2, %3" : "=v"(r) : "v"(a), "v"(b), "v"(c)); return r; }
; template <int DQK, int DV, int MODE> ...
;     ...
;             float mx = -1e30f;
; #pragma unroll
;             for (int t = 0; t < 4; ++t)
; #pragma unroll
;               for (int r = 0; r < 4; ++r) {
;                 const int j = kt * 64 + t * 16 + fq * 4 + r;
;                 float sx = S[qq][t][r] * c1;
;                 if (MODE == 1) {
;                   const int dist = qpos0 + qrow - j;
;                   sx += bias_lds[min(max(dist, 0), 2047)];
;                   if (need_mask && dist < 0) sx = -1e30f;
;                 } else if (MODE == 2) {
;                   if ((qpos0 + qrow - j) < 0) sx = -1e30f;
;                 } else {
;                   const int rel = 128 + qrow - j;
;                   sx += bias_lds[min(max(rel, 0), 128)];
;                   if (rel < 0 || rel > 128 || j < jmin) sx = -1e30f;
;                 }
;                 P[t][r] = sx;
;               }
; #pragma unroll
;             for (int t = 0; t < 4; ++t) { mx = fmax3(mx, P[t][0], P[t][1]); mx = fmax3(mx, P[t][2], P[t][3]); }
;             mx = xmax_rows(mx);
;             mn = fmax3(mrow[qi], mx, mx);
; #pragma unroll
;             for (int t = 0; t < 4; ++t) P[t] = P[t] - mn;
	v_add_u32_e32 v245, 63, v246
	v_add_u32_e32 v244, 62, v246
	v_add_u32_e32 v243, 61, v246
	v_add_u32_e32 v241, 60, v246
	v_add_u32_e32 v240, 47, v246
	v_add_u32_e32 v239, 46, v246
	v_add_u32_e32 v238, 45, v246
	v_add_u32_e32 v237, 44, v246
	v_add_u32_e32 v188, 31, v246
	v_add_u32_e32 v186, 30, v246
	v_add_u32_e32 v184, 29, v246
	v_add_u32_e32 v182, 28, v246
	v_med3_i32 v165, v245, 0, v198
	v_med3_i32 v166, v244, 0, v198
	v_med3_i32 v167, v243, 0, v198
	v_med3_i32 v168, v241, 0, v198
	v_med3_i32 v169, v240, 0, v198
	v_med3_i32 v170, v239, 0, v198
	v_med3_i32 v171, v238, 0, v198
	v_med3_i32 v172, v237, 0, v198
	v_lshl_add_u32 v165, v165, 2, 0
	v_lshl_add_u32 v166, v166, 2, 0
	v_lshl_add_u32 v167, v167, 2, 0
	v_lshl_add_u32 v168, v168, 2, 0
	v_lshl_add_u32 v169, v169, 2, 0
	v_lshl_add_u32 v170, v170, 2, 0
	v_lshl_add_u32 v171, v171, 2, 0
	v_lshl_add_u32 v172, v172, 2, 0
	ds_read_b32 v165, v165 offset:34816
	ds_read_b32 v166, v166 offset:34816
	ds_read_b32 v167, v167 offset:34816
	ds_read_b32 v168, v168 offset:34816
	ds_read_b32 v169, v169 offset:34816
	ds_read_b32 v170, v170 offset:34816
	ds_read_b32 v171, v171 offset:34816
	ds_read_b32 v172, v172 offset:34816
	v_cmp_gt_i32_e64 s[12:13], 0, v245
	s_waitcnt lgkmcnt(7)
	v_fmac_f32_e32 v165, 0x3e38aa3b, v98
	s_and_b64 s[12:13], vcc, s[12:13]
	v_cndmask_b32_e64 v98, v165, v194, s[12:13]
	v_cmp_gt_i32_e64 s[12:13], 0, v244
	s_waitcnt lgkmcnt(6)
	v_fmac_f32_e32 v166, 0x3e38aa3b, v99
	s_and_b64 s[12:13], vcc, s[12:13]
	v_cndmask_b32_e64 v99, v166, v194, s[12:13]
	v_cmp_gt_i32_e64 s[12:13], 0, v243
	s_waitcnt lgkmcnt(5)
	v_fmac_f32_e32 v167, 0x3e38aa3b, v100
	s_and_b64 s[12:13], vcc, s[12:13]
	v_cndmask_b32_e64 v100, v167, v194, s[12:13]
	v_cmp_gt_i32_e64 s[12:13], 0, v241
	s_waitcnt lgkmcnt(4)
	v_fmac_f32_e32 v168, 0x3e38aa3b, v101
	s_and_b64 s[12:13], vcc, s[12:13]
	v_cndmask_b32_e64 v101, v168, v194, s[12:13]
	v_cmp_gt_i32_e64 s[12:13], 0, v240
	s_waitcnt lgkmcnt(3)
	v_fmac_f32_e32 v169, 0x3e38aa3b, v118
	s_and_b64 s[12:13], vcc, s[12:13]
	v_cndmask_b32_e64 v118, v169, v194, s[12:13]
	v_cmp_gt_i32_e64 s[12:13], 0, v239
	s_waitcnt lgkmcnt(2)
	v_fmac_f32_e32 v170, 0x3e38aa3b, v119
	s_and_b64 s[12:13], vcc, s[12:13]
	v_cndmask_b32_e64 v119, v170, v194, s[12:13]
	v_cmp_gt_i32_e64 s[12:13], 0, v238
	s_waitcnt lgkmcnt(1)
	v_fmac_f32_e32 v171, 0x3e38aa3b, v120
	s_and_b64 s[12:13], vcc, s[12:13]
	v_cndmask_b32_e64 v120, v171, v194, s[12:13]
	v_cmp_gt_i32_e64 s[12:13], 0, v237
	s_waitcnt lgkmcnt(0)
	v_fmac_f32_e32 v172, 0x3e38aa3b, v121
	s_and_b64 s[12:13], vcc, s[12:13]
	v_add_u32_e32 v169, 15, v246
	v_add_u32_e32 v171, 14, v246
	v_add_u32_e32 v173, 13, v246
	v_add_u32_e32 v175, 12, v246
	v_cndmask_b32_e64 v121, v172, v194, s[12:13]
	v_med3_i32 v165, v188, 0, v198
	v_med3_i32 v166, v186, 0, v198
	v_med3_i32 v167, v184, 0, v198
	v_med3_i32 v168, v182, 0, v198
	v_med3_i32 v170, v169, 0, v198
	v_med3_i32 v172, v171, 0, v198
	v_med3_i32 v174, v173, 0, v198
	v_med3_i32 v176, v175, 0, v198
	v_lshl_add_u32 v165, v165, 2, 0
	v_lshl_add_u32 v166, v166, 2, 0
	v_lshl_add_u32 v167, v167, 2, 0
	v_lshl_add_u32 v168, v168, 2, 0
	v_lshl_add_u32 v170, v170, 2, 0
	v_lshl_add_u32 v172, v172, 2, 0
	v_lshl_add_u32 v174, v174, 2, 0
	v_lshl_add_u32 v176, v176, 2, 0
	ds_read_b32 v165, v165 offset:34816
	ds_read_b32 v166, v166 offset:34816
	ds_read_b32 v167, v167 offset:34816
	ds_read_b32 v168, v168 offset:34816
	ds_read_b32 v170, v170 offset:34816
	ds_read_b32 v172, v172 offset:34816
	ds_read_b32 v174, v174 offset:34816
	ds_read_b32 v176, v176 offset:34816
	v_cmp_gt_i32_e64 s[12:13], 0, v188
	s_waitcnt lgkmcnt(7)
	v_fmac_f32_e32 v165, 0x3e38aa3b, v90
	s_and_b64 s[12:13], vcc, s[12:13]
	v_cndmask_b32_e64 v90, v165, v194, s[12:13]
	v_cmp_gt_i32_e64 s[12:13], 0, v186
	s_waitcnt lgkmcnt(6)
	v_fmac_f32_e32 v166, 0x3e38aa3b, v91
	s_and_b64 s[12:13], vcc, s[12:13]
	v_cndmask_b32_e64 v91, v166, v194, s[12:13]
	v_cmp_gt_i32_e64 s[12:13], 0, v184
	s_waitcnt lgkmcnt(5)
	v_fmac_f32_e32 v167, 0x3e38aa3b, v92
	s_and_b64 s[12:13], vcc, s[12:13]
	v_cndmask_b32_e64 v92, v167, v194, s[12:13]
	v_cmp_gt_i32_e64 s[12:13], 0, v182
	s_waitcnt lgkmcnt(4)
	v_fmac_f32_e32 v168, 0x3e38aa3b, v93
	s_and_b64 s[12:13], vcc, s[12:13]
	v_cndmask_b32_e64 v93, v168, v194, s[12:13]
	v_cmp_gt_i32_e64 s[12:13], 0, v169
	s_waitcnt lgkmcnt(3)
	v_fmac_f32_e32 v170, 0x3e38aa3b, v114
	s_and_b64 s[12:13], vcc, s[12:13]
	v_max3_f32 v165, v194, v98, v99
	v_cndmask_b32_e64 v114, v170, v194, s[12:13]
	v_cmp_gt_i32_e64 s[12:13], 0, v171
	v_max3_f32 v165, v165, v100, v101
	s_waitcnt lgkmcnt(2)
	v_fmac_f32_e32 v172, 0x3e38aa3b, v115
	s_and_b64 s[12:13], vcc, s[12:13]
	v_max3_f32 v165, v165, v118, v119
	v_cndmask_b32_e64 v115, v172, v194, s[12:13]
	v_cmp_gt_i32_e64 s[12:13], 0, v173
	v_max3_f32 v165, v165, v120, v121
	s_waitcnt lgkmcnt(1)
	v_fmac_f32_e32 v174, 0x3e38aa3b, v116
	s_and_b64 s[12:13], vcc, s[12:13]
	v_max3_f32 v165, v165, v90, v91
	v_cndmask_b32_e64 v116, v174, v194, s[12:13]
	v_cmp_gt_i32_e64 s[12:13], 0, v175
	v_max3_f32 v165, v165, v92, v93
	s_waitcnt lgkmcnt(0)
	v_fmac_f32_e32 v176, 0x3e38aa3b, v117
	s_and_b64 s[12:13], vcc, s[12:13]
	v_max3_f32 v165, v165, v114, v115
	v_cndmask_b32_e64 v117, v176, v194, s[12:13]
	v_max3_f32 v165, v165, v116, v117
	s_nop 0
	v_mov_b32_e32 v166, v165
	s_nop 1
	v_permlane16_swap_b32_e32 v165, v166
	v_max3_f32 v165, v165, v166, v166
	s_nop 0
	v_mov_b32_e32 v166, v165
	s_nop 1
	v_permlane32_swap_b32_e32 v165, v166
	v_max3_f32 v165, v165, v166, v166
	s_nop 0
	v_max3_f32 v165, v236, v165, v165
	s_nop 0
	v_sub_f32_e32 v176, v98, v165
	v_sub_f32_e32 v177, v99, v165
	v_sub_f32_e32 v172, v100, v165
	v_sub_f32_e32 v173, v101, v165
	v_sub_f32_e32 v166, v118, v165
	v_sub_f32_e32 v167, v119, v165
	v_sub_f32_e32 v174, v120, v165
	v_sub_f32_e32 v175, v121, v165
	v_sub_f32_e32 v170, v90, v165
	v_sub_f32_e32 v171, v91, v165
	v_sub_f32_e32 v180, v92, v165
	v_sub_f32_e32 v181, v93, v165
	v_sub_f32_e32 v178, v114, v165
	v_sub_f32_e32 v179, v115, v165
	v_sub_f32_e32 v168, v116, v165
	v_sub_f32_e32 v169, v117, v165

; __device__ __forceinline__ unsigned pack2(float lo, float hi) { unsigned r; asm("v_cvt_pk_bf16_f32 %0, %1, %2" : "=v"(r) : "v"(lo), "v"(hi)); return r; }
; __device__ __forceinline__ f32x4 mfma16(bf16x8 a, bf16x8 b, f32x4 c) { return __builtin_amdgcn_mfma_f32_16x16x32_bf16(a, b, c, 0, 0, 0); }
; __device__ __forceinline__ float fexp2(float x) { return __builtin_amdgcn_exp2f(x); }
; #define ATT_SCHED_BARRIER __builtin_amdgcn_sched_barrier(0)
; template <int DQK, int DV, int MODE> ...
;     ...
;           f32x4 ls4 = (f32x4){0.f, 0.f, 0.f, 0.f};
; #pragma unroll
;           for (int t = 0; t < 4; ++t) {
; #pragma unroll
;             for (int r = 0; r < 4; ++r) P[t][r] = fexp2(P[t][r]);
;             ls4 += P[t];
;           }
;           lrow[qi] += (ls4[0] + ls4[1]) + (ls4[2] + ls4[3]);
; #pragma unroll
;           for (int s2 = 0; s2 < 2; ++s2) {
;             u32x4 pk;
;             pk.x = pack2(P[2 * s2][0], P[2 * s2][1]); pk.y = pack2(P[2 * s2][2], P[2 * s2][3]);
;             pk.z = pack2(P[2 * s2 + 1][0], P[2 * s2 + 1][1]); pk.w = pack2(P[2 * s2 + 1][2], P[2 * s2 + 1][3]);
;             pf[qq][s2] = __builtin_bit_cast(bf16x8, pk);
;           }
;           ATT_SCHED_BARRIER;
;         }
; #pragma unroll
;         for (int s2 = 0; s2 < 2; ++s2)
; #pragma unroll
;           for (int dt = 0; dt < NDT; ++dt) {
;             const bf16x8 vf = *(const bf16x8*)(Vt + (dt * 16 + fr) * VTS + s2 * 32 + fq * 8);
; #pragma unroll
;             for (int qq = 0; qq < QG; ++qq) O[q0 + qq][dt] = mfma16(vf, pf[qq][s2], O[q0 + qq][dt]);
;             if ((dt & (ATT_PVB - 1)) == (ATT_PVB - 1)) ATT_SCHED_BARRIER;
;           }
.Lc_skip_r2:
	v_add_f32_e32 v64, v64, v65
	v_add_f32_e32 v65, v74, v75
	v_add_f32_e32 v74, v64, v65
	v_fmac_f32_e32 v74, v165, v56
	v_cvt_pk_bf16_f32 v54, v54, v55
	v_cvt_pk_bf16_f32 v55, v58, v59
	v_cvt_pk_bf16_f32 v56, v60, v61
	v_cvt_pk_bf16_f32 v57, v62, v63
	v_cvt_pk_bf16_f32 v58, v76, v77
	v_cvt_pk_bf16_f32 v59, v78, v79
	v_cvt_pk_bf16_f32 v60, v80, v81
	v_cvt_pk_bf16_f32 v61, v82, v83
	ds_read_b128 v[62:65], v208 offset:14336
	ds_read_b128 v[76:79], v161 offset:14336
	ds_read_b128 v[80:83], v207 offset:19456
	ds_read_b128 v[112:115], v207 offset:22016
	ds_read_b128 v[116:119], v208 offset:14400
	ds_read_b128 v[140:143], v161 offset:14400
	ds_read_b128 v[144:147], v207 offset:19520
	ds_read_b128 v[148:151], v207 offset:22080
	s_waitcnt lgkmcnt(7)
	v_mfma_f32_16x16x32_bf16 v[30:33], v[62:65], v[70:73], v[30:33]
	v_mfma_f32_16x16x32_bf16 v[14:17], v[62:65], v[54:57], v[14:17]
	s_waitcnt lgkmcnt(6)
	v_mfma_f32_16x16x32_bf16 v[26:29], v[76:79], v[70:73], v[26:29]
	v_mfma_f32_16x16x32_bf16 v[10:13], v[76:79], v[54:57], v[10:13]
	s_waitcnt lgkmcnt(5)
	v_mfma_f32_16x16x32_bf16 v[22:25], v[80:83], v[70:73], v[22:25]
	v_mfma_f32_16x16x32_bf16 v[6:9], v[80:83], v[54:57], v[6:9]
	s_waitcnt lgkmcnt(4)
	v_mfma_f32_16x16x32_bf16 v[18:21], v[112:115], v[70:73], v[18:21]
	v_mfma_f32_16x16x32_bf16 v[2:5], v[112:115], v[54:57], v[2:5]
	s_waitcnt lgkmcnt(3)
	v_mfma_f32_16x16x32_bf16 v[30:33], v[116:119], v[66:69], v[30:33]
	v_mfma_f32_16x16x32_bf16 v[14:17], v[116:119], v[58:61], v[14:17]
	s_waitcnt lgkmcnt(2)
	v_mfma_f32_16x16x32_bf16 v[26:29], v[140:143], v[66:69], v[26:29]
	v_mfma_f32_16x16x32_bf16 v[10:13], v[140:143], v[58:61], v[10:13]
	s_waitcnt lgkmcnt(1)
	v_mfma_f32_16x16x32_bf16 v[22:25], v[144:147], v[66:69], v[22:25]
	v_mfma_f32_16x16x32_bf16 v[6:9], v[144:147], v[58:61], v[6:9]
	s_waitcnt lgkmcnt(0)
	v_mfma_f32_16x16x32_bf16 v[18:21], v[148:151], v[66:69], v[18:21]
	v_mfma_f32_16x16x32_bf16 v[2:5], v[148:151], v[58:61], v[2:5]
	v_mov_b32_e32 v169, v107
	v_mov_b32_e32 v166, v109
	v_mov_b32_e32 v168, v110
	v_mov_b32_e32 v165, v74

; template <int DQK, int DV, int MODE> ...
;     ...
;   for (int kt = kt_begin; kt < kt_end; ++kt) {
;     const bool more = kt + 1 < kt_end;
;     if (more) gload(kt + 1);
;     ATT_SCHED_BARRIER;
;     bf16_t* Qs2 = Qs; asm volatile("" : "+v"(Qs2));
;     if (kt >= wkb && kt < wke) {
;       int path = 1; float cb = 0.f; bool need_mask = true;
;       if (MODE == 2) { need_mask = (kt * 64 + 63) > (qpos0 + w * 32); path = need_mask ? 1 : 0; }
;       if (MODE == 1) {
;         need_mask = (kt * 64 + 63) > (qpos0 + w * 32);
;         const int dmin = (qpos0 + w * 32) - (kt * 64 + 63);
;         if (dmin >= 0) {
;           const float blo = bias_lds[min(dmin, 2047)], bhi = bias_lds[min(dmin + 94, 2047)];
;           if (((__float_as_uint(blo) ^ __float_as_uint(bhi)) & 31u) == 0u) { path = 0; cb = blo; }
;         }
;       }
;       constexpr int QG = (DV == 128) ? ATT_QG_B : 2;
; #pragma unroll
;       for (int q0 = 0; q0 < 2; q0 += QG) {
;         f32x4 S[QG][4];
; #pragma unroll
;         for (int t = 0; t < 4; ++t) {
;           {
;             const bf16x8 kf = *(const bf16x8*)(Ks + (t * 16 + fr) * KST + fq * 8);
; #pragma unroll
;             for (int qq = 0; qq < QG; ++qq) S[qq][t] = __builtin_amdgcn_mfma_f32_16x16x32_bf16(kf, *(const bf16x8*)(Qs2 + ((q0 + qq) * NKS) * 512), (f32x4){0.f, 0.f, 0.f, 0.f}, 0, 0, 0);
;           }
; #pragma unroll
;           for (int ks = 1; ks < NKS; ++ks) {
;             const bf16x8 kf = *(const bf16x8*)(Ks + (t * 16 + fr) * KST + ks * 32 + fq * 8);
; #pragma unroll
;             for (int qq = 0; qq < QG; ++qq) S[qq][t] = mfma16(kf, *(const bf16x8*)(Qs2 + ((q0 + qq) * NKS + ks) * 512), S[qq][t]);
;           }
;         }
;         ATT_SCHED_BARRIER;
;         bf16x8 pf[QG][2];
; #pragma unroll
;         for (int qq = 0; qq < QG; ++qq) {
;           const int qi = q0 + qq;
;           const int qrow = w * 32 + qi * 16 + fr;
;           f32x4 P[4];
;           float mn;
;           if (path == 0) {
;             float mx = fmax3(S[qq][0][0], S[qq][0][1], S[qq][0][2]);
;             mx = fmax3(mx, S[qq][0][3], S[qq][1][0]); mx = fmax3(mx, S[qq][1][1], S[qq][1][2]); mx = fmax3(mx, S[qq][1][3], S[qq][2][0]);
;             mx = fmax3(mx, S[qq][2][1], S[qq][2][2]); mx = fmax3(mx, S[qq][2][3], S[qq][3][0]); mx = fmax3(mx, S[qq][3][1], S[qq][3][2]);
;             mx = fmax3(mx, S[qq][3][3], mx);
;             mx = xmax_rows(mx);
.LBB0_561:
	s_lshl_b32 s4, s15, 1
	s_add_i32 s4, s4, 2
	v_lshlrev_b32_e32 v34, 1, v0
	v_lshlrev_b32_e32 v38, 1, v106
	v_lshlrev_b32_e32 v42, 1, v108
	v_lshl_add_u32 v50, v136, 1, s4
	v_lshl_add_u32 v46, v138, 1, s4
	global_load_dwordx4 v[34:37], v34, s[0:1]
	global_load_dwordx4 v[38:41], v38, s[0:1]
	global_load_dwordx4 v[42:45], v42, s[0:1]
	global_load_dwordx4 v[50:53], v50, s[2:3]
	global_load_dwordx4 v[46:49], v46, s[2:3]
	v_cmp_le_i32_e32 vcc, s17, v171
	s_and_saveexec_b64 s[12:13], vcc
	s_cbranch_execz .LBB0_560
	ds_read_b128 v[114:117], v86
	ds_read_b128 v[144:147], v86 offset:3072
	ds_read_b128 v[118:121], v86 offset:1024
	ds_read_b128 v[148:151], v86 offset:4096
	ds_read_b128 v[140:143], v86 offset:2048
	ds_read_b128 v[110:113], v86 offset:5120
	ds_read_b128 v[58:61], v157
	ds_read_b128 v[220:223], v157 offset:64
	ds_read_b128 v[224:227], v157 offset:128
	ds_read_b128 v[54:57], v158
	ds_read_b128 v[228:231], v158 offset:64
	ds_read_b128 v[232:235], v158 offset:128
	v_cmp_le_i32_e32 vcc, s15, v170
	s_waitcnt lgkmcnt(5)
	v_mfma_f32_16x16x32_bf16 v[70:73], v[58:61], v[114:117], 0
	v_mfma_f32_16x16x32_bf16 v[58:61], v[58:61], v[144:147], 0
	s_waitcnt lgkmcnt(4)
	v_mfma_f32_16x16x32_bf16 v[70:73], v[220:223], v[118:121], v[70:73]
	v_mfma_f32_16x16x32_bf16 v[58:61], v[220:223], v[148:151], v[58:61]
	s_waitcnt lgkmcnt(3)
	v_mfma_f32_16x16x32_bf16 v[70:73], v[224:227], v[140:143], v[70:73]
	v_mfma_f32_16x16x32_bf16 v[58:61], v[224:227], v[110:113], v[58:61]
	ds_read_b128 v[62:65], v159
	ds_read_b128 v[236:239], v159 offset:64
	ds_read_b128 v[240:243], v159 offset:128
	s_waitcnt lgkmcnt(5)
	v_mfma_f32_16x16x32_bf16 v[66:69], v[54:57], v[114:117], 0
	v_mfma_f32_16x16x32_bf16 v[54:57], v[54:57], v[144:147], 0
	s_waitcnt lgkmcnt(4)
	v_mfma_f32_16x16x32_bf16 v[66:69], v[228:231], v[118:121], v[66:69]
	v_mfma_f32_16x16x32_bf16 v[54:57], v[228:231], v[148:151], v[54:57]
	s_waitcnt lgkmcnt(3)
	v_mfma_f32_16x16x32_bf16 v[66:69], v[232:235], v[140:143], v[66:69]
	v_mfma_f32_16x16x32_bf16 v[54:57], v[232:235], v[110:113], v[54:57]
	ds_read_b128 v[74:77], v160
	ds_read_b128 v[244:247], v160 offset:64
	ds_read_b128 v[220:223], v160 offset:128
	s_waitcnt lgkmcnt(5)
	v_mfma_f32_16x16x32_bf16 v[78:81], v[62:65], v[114:117], 0
	v_mfma_f32_16x16x32_bf16 v[62:65], v[62:65], v[144:147], 0
	s_waitcnt lgkmcnt(4)
	v_mfma_f32_16x16x32_bf16 v[78:81], v[236:239], v[118:121], v[78:81]
	v_mfma_f32_16x16x32_bf16 v[62:65], v[236:239], v[148:151], v[62:65]
	s_waitcnt lgkmcnt(3)
	v_mfma_f32_16x16x32_bf16 v[78:81], v[240:243], v[140:143], v[78:81]
	v_mfma_f32_16x16x32_bf16 v[62:65], v[240:243], v[110:113], v[62:65]
	s_waitcnt lgkmcnt(2)
	v_mfma_f32_16x16x32_bf16 v[82:85], v[74:77], v[114:117], 0
	v_mfma_f32_16x16x32_bf16 v[74:77], v[74:77], v[144:147], 0
	s_waitcnt lgkmcnt(1)
	v_mfma_f32_16x16x32_bf16 v[82:85], v[244:247], v[118:121], v[82:85]
	v_mfma_f32_16x16x32_bf16 v[74:77], v[244:247], v[148:151], v[74:77]
	s_waitcnt lgkmcnt(0)
	v_mfma_f32_16x16x32_bf16 v[82:85], v[220:223], v[140:143], v[82:85]
	v_mfma_f32_16x16x32_bf16 v[74:77], v[220:223], v[110:113], v[74:77]
	s_and_saveexec_b64 s[4:5], vcc
	s_xor_b64 s[4:5], exec, s[4:5]
	s_cbranch_execz .LBB0_564
	v_max3_f32 v107, v70, v71, v72
	s_mov_b32 s6, 0x3e16c740
	v_max3_f32 v107, v107, v73, v66
	v_max3_f32 v107, v107, v67, v68
	v_max3_f32 v107, v107, v69, v78
	v_max3_f32 v107, v107, v79, v80
	v_max3_f32 v107, v107, v81, v82
	v_max3_f32 v107, v107, v83, v84
	v_max3_f32 v107, v107, v85, v107
	v_mov_b32_e32 v109, v107
	s_nop 1
	v_permlane16_swap_b32_e32 v107, v109
	v_max3_f32 v107, v107, v109, v109
	v_mov_b32_e32 v109, v107
	s_nop 1
	v_permlane32_swap_b32_e32 v107, v109
	v_max3_f32 v107, v107, v109, v109
	v_fma_f32 v107, v107, s6, 0
	v_max3_f32 v107, v169, v107, v169
	v_sub_f32_e32 v116, 0, v107
	v_pk_fma_f32 v[118:119], v[84:85], s[6:7], v[116:117] op_sel_hi:[1,0,0]
	v_pk_fma_f32 v[120:121], v[82:83], s[6:7], v[116:117] op_sel_hi:[1,0,0]
	v_pk_fma_f32 v[140:141], v[80:81], s[6:7], v[116:117] op_sel_hi:[1,0,0]
	v_pk_fma_f32 v[110:111], v[78:79], s[6:7], v[116:117] op_sel_hi:[1,0,0]
	v_pk_fma_f32 v[114:115], v[68:69], s[6:7], v[116:117] op_sel_hi:[1,0,0]
	v_pk_fma_f32 v[142:143], v[66:67], s[6:7], v[116:117] op_sel_hi:[1,0,0]
	v_pk_fma_f32 v[112:113], v[72:73], s[6:7], v[116:117] op_sel_hi:[1,0,0]
	v_pk_fma_f32 v[116:117], v[70:71], s[6:7], v[116:117] op_sel_hi:[1,0,0]

; __device__ __forceinline__ f32x4 mfma16(bf16x8 a, bf16x8 b, f32x4 c) { return __builtin_amdgcn_mfma_f32_16x16x32_bf16(a, b, c, 0, 0, 0); }
; template <int DQK, int DV, int MODE> ...
;     ...
;         for (int t = 0; t < 4; ++t) {
;           {
;             const bf16x8 kf = *(const bf16x8*)(Ks + (t * 16 + fr) * KST + fq * 8);
; #pragma unroll
;             for (int qq = 0; qq < QG; ++qq) S[qq][t] = __builtin_amdgcn_mfma_f32_16x16x32_bf16(kf, *(const bf16x8*)(Qs2 + ((q0 + qq) * NKS) * 512), (f32x4){0.f, 0.f, 0.f, 0.f}, 0, 0, 0);
;           }
; #pragma unroll
;           for (int ks = 1; ks < NKS; ++ks) {
;             const bf16x8 kf = *(const bf16x8*)(Ks + (t * 16 + fr) * KST + ks * 32 + fq * 8);
; #pragma unroll
;             for (int qq = 0; qq < QG; ++qq) S[qq][t] = mfma16(kf, *(const bf16x8*)(Qs2 + ((q0 + qq) * NKS + ks) * 512), S[qq][t]);
;           }
;         }
;     ...
;                 } else {
;                   const int rel = 128 + qrow - j;
;                   sx += bias_lds[min(max(rel, 0), 128)];
;                   if (rel < 0 || rel > 128 || j < jmin) sx = -1e30f;
.LBB0_601:
	v_cmp_ge_u32_e32 vcc, s0, v112
	v_cmp_le_i32_e64 s[14:15], s0, v89
	v_mov_b64_e32 v[2:3], v[124:125]
	s_and_b64 s[4:5], vcc, s[14:15]
	s_and_saveexec_b64 s[78:79], s[4:5]
	s_cbranch_execz .LBB0_706
	ds_read_b128 v[136:139], v2
	ds_read_b128 v[144:147], v2 offset:2048
	ds_read_b128 v[64:67], v207
	ds_read_b128 v[140:143], v2 offset:1024
	ds_read_b128 v[156:159], v2 offset:3072
	ds_read_b128 v[160:163], v207 offset:64
	ds_read_b128 v[60:63], v207 offset:2560
	ds_read_b128 v[164:167], v207 offset:2624
	ds_read_b128 v[56:59], v207 offset:5120
	ds_read_b128 v[52:55], v207 offset:7680
	v_readlane_b32 s4, v255, 1
	s_waitcnt lgkmcnt(7)
	v_mfma_f32_16x16x32_bf16 v[80:83], v[64:67], v[136:139], 0
	v_mfma_f32_16x16x32_bf16 v[64:67], v[64:67], v[144:147], 0
	s_waitcnt lgkmcnt(4)
	v_mfma_f32_16x16x32_bf16 v[80:83], v[160:163], v[140:143], v[80:83]
	v_mfma_f32_16x16x32_bf16 v[64:67], v[160:163], v[156:159], v[64:67]
	ds_read_b128 v[160:163], v207 offset:5184
	s_waitcnt lgkmcnt(4)
	v_mfma_f32_16x16x32_bf16 v[76:79], v[60:63], v[136:139], 0
	v_mfma_f32_16x16x32_bf16 v[60:63], v[60:63], v[144:147], 0
	s_waitcnt lgkmcnt(3)
	v_mfma_f32_16x16x32_bf16 v[76:79], v[164:167], v[140:143], v[76:79]
	v_mfma_f32_16x16x32_bf16 v[60:63], v[164:167], v[156:159], v[60:63]
	ds_read_b128 v[164:167], v207 offset:7744
	s_waitcnt lgkmcnt(3)
	v_mfma_f32_16x16x32_bf16 v[72:75], v[56:59], v[136:139], 0
	v_mfma_f32_16x16x32_bf16 v[56:59], v[56:59], v[144:147], 0
	s_waitcnt lgkmcnt(1)
	v_mfma_f32_16x16x32_bf16 v[72:75], v[160:163], v[140:143], v[72:75]
	v_mfma_f32_16x16x32_bf16 v[56:59], v[160:163], v[156:159], v[56:59]
	v_mfma_f32_16x16x32_bf16 v[68:71], v[52:55], v[136:139], 0
	v_mfma_f32_16x16x32_bf16 v[52:55], v[52:55], v[144:147], 0
	s_waitcnt lgkmcnt(0)
	v_mfma_f32_16x16x32_bf16 v[68:71], v[164:167], v[140:143], v[68:71]
	v_mfma_f32_16x16x32_bf16 v[52:55], v[164:167], v[156:159], v[52:55]
	v_add_u32_e32 v94, s4, v91
	s_branch .La_q1
	v_add_u32_e32 v136, s33, v114
	v_add_u32_e32 v0, 0x80, v136
	s_movk_i32 s4, 0x80
	v_cmp_lt_u32_e64 s[80:81], s4, v0
	s_movk_i32 s4, 0x81
	v_cmp_gt_u32_e32 vcc, s4, v0
	v_add_u32_e32 v0, v113, v93
	v_cmp_gt_u32_e64 s[38:39], s1, v94
	s_mov_b64 s[6:7], s[80:81]
	s_and_saveexec_b64 s[4:5], vcc
	s_cbranch_execz .LBB0_604
	ds_read_b32 v2, v0 offset:35328
	s_andn2_b64 s[6:7], s[80:81], exec
	s_and_b64 s[8:9], s[38:39], exec
	s_or_b64 s[6:7], s[6:7], s[8:9]
	s_waitcnt lgkmcnt(0)
	v_fmac_f32_e32 v2, 0x3e38aa3b, v80

; __device__ __forceinline__ unsigned pack2(float lo, float hi) { unsigned r; asm("v_cvt_pk_bf16_f32 %0, %1, %2" : "=v"(r) : "v"(lo), "v"(hi)); return r; }
; __device__ __forceinline__ f32x4 mfma16(bf16x8 a, bf16x8 b, f32x4 c) { return __builtin_amdgcn_mfma_f32_16x16x32_bf16(a, b, c, 0, 0, 0); }
; __device__ __forceinline__ float fexp2(float x) { return __builtin_amdgcn_exp2f(x); }
; __device__ __forceinline__ float fmax3(float a, float b, float c) { float r; asm("v_max3_f32 %0, %1, %2, %3" : "=v"(r) : "v"(a), "v"(b), "v"(c)); return r; }
; #define ATT_SCHED_BARRIER __builtin_amdgcn_sched_barrier(0)
; template <int DQK, int DV, int MODE> ...
;     ...
; #pragma unroll
;             for (int t = 0; t < 4; ++t) { mx = fmax3(mx, P[t][0], P[t][1]); mx = fmax3(mx, P[t][2], P[t][3]); }
;             mx = xmax_rows(mx);
;             mn = fmax3(mrow[qi], mx, mx);
; #pragma unroll
;             for (int t = 0; t < 4; ++t) P[t] = P[t] - mn;
;           }
;           {
;             const float alpha = fexp2(mrow[qi] - mn);
;             lrow[qi] *= alpha;
; #pragma unroll
;             for (int dt = 0; dt < NDT; ++dt) O[qi][dt] *= alpha;
;           }
;           mrow[qi] = mn;
;           f32x4 ls4 = (f32x4){0.f, 0.f, 0.f, 0.f};
; #pragma unroll
;           for (int t = 0; t < 4; ++t) {
; #pragma unroll
;             for (int r = 0; r < 4; ++r) P[t][r] = fexp2(P[t][r]);
;             ls4 += P[t];
;           }
;           lrow[qi] += (ls4[0] + ls4[1]) + (ls4[2] + ls4[3]);
; #pragma unroll
;           for (int s2 = 0; s2 < 2; ++s2) {
;             u32x4 pk;
;             pk.x = pack2(P[2 * s2][0], P[2 * s2][1]); pk.y = pack2(P[2 * s2][2], P[2 * s2][3]);
;             pk.z = pack2(P[2 * s2 + 1][0], P[2 * s2 + 1][1]); pk.w = pack2(P[2 * s2 + 1][2], P[2 * s2 + 1][3]);
;             pf[qq][s2] = __builtin_bit_cast(bf16x8, pk);
;           }
;           ATT_SCHED_BARRIER;
;         }
; #pragma unroll
;         for (int s2 = 0; s2 < 2; ++s2)
; #pragma unroll
;           for (int dt = 0; dt < NDT; ++dt) {
;             const bf16x8 vf = *(const bf16x8*)(Vt + (dt * 16 + fr) * VTS + s2 * 32 + fq * 8);
; #pragma unroll
;             for (int qq = 0; qq < QG; ++qq) O[q0 + qq][dt] = mfma16(vf, pf[qq][s2], O[q0 + qq][dt]);
.La_q2_join:
	v_pk_add_f32 v[98:99], v[98:99], 0 op_sel_hi:[1,0]
	v_pk_add_f32 v[94:95], v[94:95], 0 op_sel_hi:[1,0]
	v_sub_f32_e32 v0, v120, v121
	v_pk_add_f32 v[94:95], v[96:97], v[94:95]
	v_pk_add_f32 v[78:79], v[78:79], v[98:99]
	v_exp_f32_e32 v0, v0
	v_pk_add_f32 v[78:79], v[82:83], v[78:79]
	v_pk_add_f32 v[76:77], v[76:77], v[94:95]
	v_pk_add_f32 v[2:3], v[2:3], v[78:79]
	v_pk_add_f32 v[76:77], v[80:81], v[76:77]
	v_add_f32_e32 v2, v2, v3
	v_add_f32_e32 v3, v76, v77
	v_add_f32_e32 v82, v2, v3
	v_pk_mul_f32 v[50:51], v[50:51], v[0:1] op_sel_hi:[1,0]
	v_pk_mul_f32 v[48:49], v[48:49], v[0:1] op_sel_hi:[1,0]
	v_pk_mul_f32 v[46:47], v[46:47], v[0:1] op_sel_hi:[1,0]
	v_pk_mul_f32 v[44:45], v[44:45], v[0:1] op_sel_hi:[1,0]
	v_pk_mul_f32 v[42:43], v[42:43], v[0:1] op_sel_hi:[1,0]
	v_pk_mul_f32 v[40:41], v[40:41], v[0:1] op_sel_hi:[1,0]
	v_pk_mul_f32 v[38:39], v[38:39], v[0:1] op_sel_hi:[1,0]
	v_pk_mul_f32 v[36:37], v[36:37], v[0:1] op_sel_hi:[1,0]
	v_fmac_f32_e32 v82, v119, v0
	v_max3_f32 v0, v194, v137, v64
	s_nop 0
	v_max3_f32 v0, v0, v65, v66
	s_nop 0
	v_max3_f32 v0, v0, v67, v60
	s_nop 0
	v_max3_f32 v0, v0, v61, v62
	s_nop 0
	v_max3_f32 v0, v0, v63, v56
	s_nop 0
	v_max3_f32 v0, v0, v57, v58
	s_nop 0
	v_max3_f32 v0, v0, v59, v136
	s_nop 0
	v_max3_f32 v0, v0, v53, v54
	s_nop 0
	v_mov_b32_e32 v2, v0
	s_nop 1
	v_permlane16_swap_b32_e32 v0, v2
	v_max3_f32 v0, v0, v2, v2
	s_nop 0
	v_mov_b32_e32 v2, v0
	s_nop 1
	v_permlane32_swap_b32_e32 v0, v2
	v_max3_f32 v0, v0, v2, v2
	s_nop 0
	v_max3_f32 v52, v118, v0, v0
	s_nop 0
	v_sub_f32_e32 v55, v66, v52
	v_sub_f32_e32 v65, v65, v52
	v_sub_f32_e32 v3, v64, v52
	v_sub_f32_e32 v2, v137, v52
	v_sub_f32_e32 v62, v62, v52
	v_sub_f32_e32 v61, v61, v52
	v_sub_f32_e32 v64, v60, v52
	v_sub_f32_e32 v60, v67, v52
	v_sub_f32_e32 v66, v57, v52
	v_sub_f32_e32 v76, v56, v52
	v_exp_f32_e32 v2, v2
	v_exp_f32_e32 v3, v3
	v_exp_f32_e32 v56, v65
	v_exp_f32_e32 v57, v55
	v_sub_f32_e32 v67, v58, v52
	v_sub_f32_e32 v77, v63, v52
	v_sub_f32_e32 v78, v59, v52
	v_exp_f32_e32 v58, v60
	v_exp_f32_e32 v60, v61
	v_exp_f32_e32 v61, v62
	v_exp_f32_e32 v59, v64
	v_sub_f32_e32 v79, v54, v52
	v_sub_f32_e32 v53, v53, v52
	v_sub_f32_e32 v80, v136, v52
	v_exp_f32_e32 v64, v77
	v_exp_f32_e32 v65, v76
	v_exp_f32_e32 v66, v66
	v_exp_f32_e32 v67, v67
	v_exp_f32_e32 v76, v78
	v_exp_f32_e32 v78, v53
	v_exp_f32_e32 v79, v79
	v_exp_f32_e32 v77, v80
	v_pk_add_f32 v[54:55], v[2:3], 0 op_sel_hi:[1,0]
	v_pk_add_f32 v[62:63], v[56:57], 0 op_sel_hi:[1,0]
	v_sub_f32_e32 v0, v118, v52
	v_pk_add_f32 v[62:63], v[60:61], v[62:63]
	v_pk_add_f32 v[54:55], v[58:59], v[54:55]
	v_exp_f32_e32 v0, v0
	v_pk_add_f32 v[54:55], v[64:65], v[54:55]
	v_pk_add_f32 v[62:63], v[66:67], v[62:63]
	v_pk_add_f32 v[54:55], v[76:77], v[54:55]
	v_pk_add_f32 v[62:63], v[78:79], v[62:63]
	v_pk_mul_f32 v[18:19], v[18:19], v[0:1] op_sel_hi:[1,0]
	v_pk_mov_b32 v[80:81], v[54:55], v[62:63] op_sel:[1,0]
	v_mov_b32_e32 v55, v63
	v_pk_add_f32 v[54:55], v[80:81], v[54:55]
	v_pk_mul_f32 v[16:17], v[16:17], v[0:1] op_sel_hi:[1,0]
	v_pk_mul_f32 v[14:15], v[14:15], v[0:1] op_sel_hi:[1,0]
	v_pk_mul_f32 v[12:13], v[12:13], v[0:1] op_sel_hi:[1,0]
	v_pk_mul_f32 v[10:11], v[10:11], v[0:1] op_sel_hi:[1,0]
	v_pk_mul_f32 v[8:9], v[8:9], v[0:1] op_sel_hi:[1,0]
	v_pk_mul_f32 v[6:7], v[6:7], v[0:1] op_sel_hi:[1,0]
	v_pk_mul_f32 v[4:5], v[4:5], v[0:1] op_sel_hi:[1,0]
	v_add_f32_e32 v53, v54, v55
	v_fmac_f32_e32 v53, v117, v0
	v_cvt_pk_bf16_f32 v54, v2, v3
	v_cvt_pk_bf16_f32 v55, v56, v57
	v_cvt_pk_bf16_f32 v56, v58, v59
	v_cvt_pk_bf16_f32 v57, v60, v61
	v_cvt_pk_bf16_f32 v58, v64, v65
	v_cvt_pk_bf16_f32 v59, v66, v67
	v_cvt_pk_bf16_f32 v60, v76, v77
	v_cvt_pk_bf16_f32 v61, v78, v79
	ds_read_b128 v[156:159], v208 offset:14336
	ds_read_b128 v[160:163], v208 offset:16896
	ds_read_b128 v[164:167], v208 offset:19456
	ds_read_b128 v[168:171], v208 offset:22016
	ds_read_b128 v[172:175], v208 offset:14400
	ds_read_b128 v[176:179], v208 offset:16960
	ds_read_b128 v[180:183], v208 offset:19520
	ds_read_b128 v[184:187], v208 offset:22080
	s_waitcnt lgkmcnt(7)
	v_mfma_f32_16x16x32_bf16 v[48:51], v[156:159], v[72:75], v[48:51]
	v_mfma_f32_16x16x32_bf16 v[16:19], v[156:159], v[54:57], v[16:19]
	s_waitcnt lgkmcnt(6)
	v_mfma_f32_16x16x32_bf16 v[44:47], v[160:163], v[72:75], v[44:47]
	v_mfma_f32_16x16x32_bf16 v[12:15], v[160:163], v[54:57], v[12:15]
	s_waitcnt lgkmcnt(5)
	v_mfma_f32_16x16x32_bf16 v[40:43], v[164:167], v[72:75], v[40:43]
	v_mfma_f32_16x16x32_bf16 v[8:11], v[164:167], v[54:57], v[8:11]
	s_waitcnt lgkmcnt(4)
	v_mfma_f32_16x16x32_bf16 v[36:39], v[168:171], v[72:75], v[36:39]
	v_mfma_f32_16x16x32_bf16 v[2:5], v[168:171], v[54:57], v[4:7]
	s_waitcnt lgkmcnt(3)
	v_mfma_f32_16x16x32_bf16 v[48:51], v[172:175], v[68:71], v[48:51]
	v_mfma_f32_16x16x32_bf16 v[16:19], v[172:175], v[58:61], v[16:19]
	s_waitcnt lgkmcnt(2)
	v_mfma_f32_16x16x32_bf16 v[44:47], v[176:179], v[68:71], v[44:47]
	v_mfma_f32_16x16x32_bf16 v[12:15], v[176:179], v[58:61], v[12:15]
	s_waitcnt lgkmcnt(1)
	v_mfma_f32_16x16x32_bf16 v[40:43], v[180:183], v[68:71], v[40:43]
	v_mfma_f32_16x16x32_bf16 v[8:11], v[180:183], v[58:61], v[8:11]
	s_waitcnt lgkmcnt(0)
	v_mfma_f32_16x16x32_bf16 v[36:39], v[184:187], v[68:71], v[36:39]
	v_mfma_f32_16x16x32_bf16 v[4:7], v[184:187], v[58:61], v[2:5]
	v_mov_b32_e32 v120, v121
	v_mov_b32_e32 v118, v52
	v_mov_b32_e32 v119, v82
	v_mov_b32_e32 v117, v53
